# attention loop: cross-half row-max merge (v_mov+permlane32_swap+v_max) moved from every tile into the rare rescale path; trigger test done per lane half
# speedup vs baseline: 1.0037x; 1.0037x over previous
.LBB0_842:
	s_lshl_b32 s0, s36, 1
	v_add_u32_e32 v200, s0, v211
	s_setprio 1
	ds_read_b64_tr_b16 v[196:197], v200 offset:24576
	ds_read_b64_tr_b16 v[198:199], v200 offset:25088
	v_add_f32_e32 v100, v80, v81
	v_add_f32_e32 v100, v82, v100
	v_add_f32_e32 v100, v83, v100
	v_add_f32_e32 v100, v84, v100
	v_add_f32_e32 v116, v85, v100
	s_waitcnt lgkmcnt(9)
	v_mfma_f32_32x32x16_bf16 v[96:111], v[96:99], v[156:159], v[236:251]
	v_cvt_pk_bf16_f32 v140, v80, v81
	v_cvt_pk_bf16_f32 v141, v82, v83
	ds_read_b64_tr_b16 v[188:189], v200 offset:28672
	ds_read_b64_tr_b16 v[190:191], v200 offset:29184
	v_add_f32_e32 v80, v86, v116
	v_add_f32_e32 v80, v87, v80
	v_add_f32_e32 v80, v88, v80
	v_add_f32_e32 v80, v89, v80
	v_cvt_pk_bf16_f32 v142, v84, v85
	v_cvt_pk_bf16_f32 v143, v86, v87
	s_waitcnt lgkmcnt(10)
	v_mfma_f32_32x32x16_bf16 v[112:127], v[112:115], v[156:159], v[236:251]
	ds_read_b64_tr_b16 v[184:185], v200 offset:25600
	ds_read_b64_tr_b16 v[186:187], v200 offset:26112
	s_waitcnt lgkmcnt(11)
	v_mfma_f32_32x32x16_bf16 v[96:111], v[180:183], v[152:155], v[96:111]
	v_add_f32_e32 v80, v90, v80
	v_add_f32_e32 v80, v91, v80
	v_add_f32_e32 v80, v92, v80
	v_add_f32_e32 v80, v93, v80
	v_cvt_pk_bf16_f32 v136, v88, v89
	v_cvt_pk_bf16_f32 v137, v90, v91
	ds_read_b64_tr_b16 v[180:181], v200 offset:29696
	ds_read_b64_tr_b16 v[182:183], v200 offset:30208
	v_add_f32_e32 v80, v94, v80
	v_add_f32_e32 v80, v95, v80
	v_add_f32_e32 v80, v64, v80
	v_add_f32_e32 v80, v65, v80
	v_cvt_pk_bf16_f32 v138, v92, v93
	v_cvt_pk_bf16_f32 v139, v94, v95
	s_waitcnt lgkmcnt(12)
	v_mfma_f32_32x32x16_bf16 v[112:127], v[176:179], v[152:155], v[112:127]
	ds_read_b64_tr_b16 v[192:193], v200 offset:26624
	ds_read_b64_tr_b16 v[194:195], v200 offset:27136
	s_waitcnt lgkmcnt(13)
	v_mfma_f32_32x32x16_bf16 v[96:111], v[172:175], v[148:151], v[96:111]
	v_add_f32_e32 v80, v66, v80
	v_add_f32_e32 v80, v67, v80
	v_add_f32_e32 v80, v68, v80
	v_add_f32_e32 v80, v69, v80
	v_cvt_pk_bf16_f32 v132, v64, v65
	v_cvt_pk_bf16_f32 v133, v66, v67
	ds_read_b64_tr_b16 v[172:173], v200 offset:30720
	ds_read_b64_tr_b16 v[174:175], v200 offset:31232
	v_add_f32_e32 v64, v70, v80
	v_add_f32_e32 v64, v71, v64
	v_add_f32_e32 v64, v72, v64
	v_add_f32_e32 v64, v73, v64
	v_cvt_pk_bf16_f32 v134, v68, v69
	v_cvt_pk_bf16_f32 v135, v70, v71
	s_waitcnt lgkmcnt(14)
	v_mfma_f32_32x32x16_bf16 v[112:127], v[168:171], v[148:151], v[112:127]
	ds_read_b64_tr_b16 v[168:169], v200 offset:27648
	ds_read_b64_tr_b16 v[170:171], v200 offset:28160
	s_waitcnt lgkmcnt(14)
	v_mfma_f32_32x32x16_bf16 v[96:111], v[164:167], v[144:147], v[96:111]
	v_add_f32_e32 v64, v74, v64
	v_add_f32_e32 v64, v75, v64
	v_add_f32_e32 v64, v76, v64
	v_add_f32_e32 v64, v77, v64
	v_cvt_pk_bf16_f32 v128, v72, v73
	v_cvt_pk_bf16_f32 v129, v74, v75
	ds_read_b64_tr_b16 v[176:177], v200 offset:31744
	ds_read_b64_tr_b16 v[178:179], v200 offset:32256
	v_add_f32_e32 v64, v78, v64
	v_mfma_f32_32x32x16_bf16 v[112:127], v[160:163], v[144:147], v[112:127]
	v_add_f32_e32 v160, v79, v64
	v_cvt_pk_bf16_f32 v130, v76, v77
	v_cvt_pk_bf16_f32 v131, v78, v79
	s_setprio 0
	s_add_i32 s0, s23, s26
	s_mov_b32 s1, m0
	s_mov_b32 m0, s0
	s_nop 0
	global_load_lds_dwordx4 v230, s[98:99]
	s_add_u32 s98, s98, 0x20000
	s_addc_u32 s99, s99, 0
	s_mov_b32 m0, s1
	s_lshl_b32 s0, s22, 1
	s_add_i32 s0, s0, s27
	s_mov_b32 s1, m0
	s_mov_b32 m0, s0
	s_nop 0
	global_load_lds_dwordx4 v228, s[86:87]
	s_add_u32 s86, s86, 0x20000
	s_addc_u32 s87, s87, 0
	s_mov_b32 m0, s1
	s_addk_i32 s0, 0x2000
	s_mov_b32 s1, m0
	s_mov_b32 m0, s0
	s_nop 0
	global_load_lds_dwordx4 v206, s[90:91]
	s_add_u32 s90, s90, 0x20000
	s_addc_u32 s91, s91, 0
	s_mov_b32 m0, s1
	v_max_f32_e32 v80, v96, v97
	v_max3_f32 v81, v98, v99, v113
	v_max3_f32 v80, v80, v112, v114
	v_max3_f32 v80, v80, v115, v100
	v_max3_f32 v81, v81, v102, v103
	v_max3_f32 v80, v80, v101, v116
	v_max3_f32 v81, v81, v118, v119
	v_max3_f32 v80, v80, v117, v104
	v_max3_f32 v81, v81, v106, v107
	v_max3_f32 v80, v80, v105, v120
	v_max3_f32 v81, v81, v122, v123
	v_max3_f32 v80, v80, v121, v108
	v_max3_f32 v81, v81, v110, v111
	v_max3_f32 v80, v80, v109, v124
	v_max3_f32 v81, v81, v126, v127
	v_max3_f32 v80, v80, v125, v81
	v_cmp_lt_f32_e32 vcc, s56, v80
	s_cmp_lg_u64 vcc, 0
	v_add_f32_e32 v215, v215, v160
	s_cselect_b64 s[0:1], -1, 0
	s_cbranch_vccnz .LBB0_850

.LBB0_845:
	s_add_i32 s0, s22, 0x2000
	s_cmpk_lg_i32 s22, 0x4000
	s_cselect_b32 s24, s0, 0
	s_lshl_b32 s0, s23, 1
	v_add_u32_e32 v255, s0, v211
	s_setprio 1
	ds_read_b64_tr_b16 v[200:201], v255 offset:24576
	ds_read_b64_tr_b16 v[202:203], v255 offset:25088
	v_add_f32_e32 v100, v80, v81
	v_add_f32_e32 v100, v82, v100
	v_add_f32_e32 v100, v83, v100
	v_add_f32_e32 v100, v84, v100
	v_add_f32_e32 v116, v85, v100
	v_mfma_f32_32x32x16_bf16 v[96:111], v[96:99], v[156:159], v[236:251]
	v_cvt_pk_bf16_f32 v140, v80, v81
	v_cvt_pk_bf16_f32 v141, v82, v83
	ds_read_b64_tr_b16 v[176:177], v255 offset:28672
	ds_read_b64_tr_b16 v[178:179], v255 offset:29184
	v_add_f32_e32 v80, v86, v116
	v_add_f32_e32 v80, v87, v80
	v_add_f32_e32 v80, v88, v80
	v_add_f32_e32 v80, v89, v80
	v_cvt_pk_bf16_f32 v142, v84, v85
	v_cvt_pk_bf16_f32 v143, v86, v87
	v_mfma_f32_32x32x16_bf16 v[112:127], v[112:115], v[156:159], v[236:251]
	ds_read_b64_tr_b16 v[168:169], v255 offset:25600
	ds_read_b64_tr_b16 v[170:171], v255 offset:26112
	v_mfma_f32_32x32x16_bf16 v[96:111], v[196:199], v[152:155], v[96:111]
	v_add_f32_e32 v80, v90, v80
	v_add_f32_e32 v80, v91, v80
	v_add_f32_e32 v80, v92, v80
	v_add_f32_e32 v80, v93, v80
	v_cvt_pk_bf16_f32 v136, v88, v89
	v_cvt_pk_bf16_f32 v137, v90, v91
	ds_read_b64_tr_b16 v[172:173], v255 offset:29696
	ds_read_b64_tr_b16 v[174:175], v255 offset:30208
	v_add_f32_e32 v80, v94, v80
	v_add_f32_e32 v80, v95, v80
	v_add_f32_e32 v80, v64, v80
	v_add_f32_e32 v80, v65, v80
	v_cvt_pk_bf16_f32 v138, v92, v93
	v_cvt_pk_bf16_f32 v139, v94, v95
	v_mfma_f32_32x32x16_bf16 v[112:127], v[188:191], v[152:155], v[112:127]
	ds_read_b64_tr_b16 v[196:197], v255 offset:26624
	ds_read_b64_tr_b16 v[198:199], v255 offset:27136
	v_mfma_f32_32x32x16_bf16 v[96:111], v[184:187], v[148:151], v[96:111]
	v_add_f32_e32 v80, v66, v80
	v_add_f32_e32 v80, v67, v80
	v_add_f32_e32 v80, v68, v80
	v_add_f32_e32 v80, v69, v80
	v_cvt_pk_bf16_f32 v132, v64, v65
	v_cvt_pk_bf16_f32 v133, v66, v67
	ds_read_b64_tr_b16 v[184:185], v255 offset:30720
	ds_read_b64_tr_b16 v[186:187], v255 offset:31232
	v_add_f32_e32 v64, v70, v80
	v_add_f32_e32 v64, v71, v64
	v_add_f32_e32 v64, v72, v64
	v_add_f32_e32 v64, v73, v64
	v_cvt_pk_bf16_f32 v134, v68, v69
	v_cvt_pk_bf16_f32 v135, v70, v71
	v_mfma_f32_32x32x16_bf16 v[112:127], v[164:167], v[148:151], v[112:127]
	ds_read_b64_tr_b16 v[188:189], v255 offset:27648
	ds_read_b64_tr_b16 v[190:191], v255 offset:28160
	v_mfma_f32_32x32x16_bf16 v[96:111], v[180:183], v[144:147], v[96:111]
	v_add_f32_e32 v64, v74, v64
	v_add_f32_e32 v64, v75, v64
	v_add_f32_e32 v64, v76, v64
	v_add_f32_e32 v64, v77, v64
	v_cvt_pk_bf16_f32 v128, v72, v73
	v_cvt_pk_bf16_f32 v129, v74, v75
	ds_read_b64_tr_b16 v[192:193], v255 offset:31744
	ds_read_b64_tr_b16 v[194:195], v255 offset:32256
	v_add_f32_e32 v64, v78, v64
	v_mfma_f32_32x32x16_bf16 v[112:127], v[160:163], v[144:147], v[112:127]
	v_add_f32_e32 v160, v79, v64
	v_cvt_pk_bf16_f32 v130, v76, v77
	v_cvt_pk_bf16_f32 v131, v78, v79
	s_setprio 0
	s_add_i32 s0, s22, s26
	s_mov_b32 s1, m0
	s_mov_b32 m0, s0
	s_nop 0
	global_load_lds_dwordx4 v230, s[98:99]
	s_add_u32 s98, s98, 0x20000
	s_addc_u32 s99, s99, 0
	s_mov_b32 m0, s1
	s_lshl_b32 s0, s24, 1
	s_add_i32 s0, s0, s27
	s_mov_b32 s1, m0
	s_mov_b32 m0, s0
	s_nop 0
	global_load_lds_dwordx4 v228, s[86:87]
	s_add_u32 s86, s86, 0x20000
	s_addc_u32 s87, s87, 0
	s_mov_b32 m0, s1
	s_addk_i32 s0, 0x2000
	s_mov_b32 s1, m0
	s_mov_b32 m0, s0
	s_nop 0
	global_load_lds_dwordx4 v206, s[90:91]
	s_add_u32 s90, s90, 0x20000
	s_addc_u32 s91, s91, 0
	s_mov_b32 m0, s1
	v_max_f32_e32 v80, v96, v97
	v_max3_f32 v81, v98, v99, v113
	v_max3_f32 v80, v80, v112, v114
	v_max3_f32 v80, v80, v115, v100
	v_max3_f32 v81, v81, v102, v103
	v_max3_f32 v80, v80, v101, v116
	v_max3_f32 v81, v81, v118, v119
	v_max3_f32 v80, v80, v117, v104
	v_max3_f32 v81, v81, v106, v107
	v_max3_f32 v80, v80, v105, v120
	v_max3_f32 v81, v81, v122, v123
	v_max3_f32 v80, v80, v121, v108
	v_max3_f32 v81, v81, v110, v111
	v_max3_f32 v80, v80, v109, v124
	v_max3_f32 v81, v81, v126, v127
	v_max3_f32 v80, v80, v125, v81
	v_cmp_lt_f32_e32 vcc, s56, v80
	s_cmp_lg_u64 vcc, 0
	v_add_f32_e32 v215, v215, v160
	s_cselect_b64 s[0:1], -1, 0
	s_cbranch_vccnz .LBB0_853

.LBB0_850:
	v_mov_b32_e32 v81, v80
	s_nop 1
	v_permlane32_swap_b32_e32 v80, v81
	v_max_f32_e32 v80, v80, v81
	v_max_f32_e32 v80, v80, v80
	v_max_f32_e32 v81, 0, v80
	v_exp_f32_e64 v80, -v81
	s_and_saveexec_b64 s[14:15], s[6:7]
	ds_write_b32 v212, v80
	s_or_b64 exec, exec, s[14:15]
	v_sub_f32_e32 v96, v96, v81
	v_sub_f32_e32 v97, v97, v81
	v_sub_f32_e32 v98, v98, v81
	v_sub_f32_e32 v99, v99, v81
	v_sub_f32_e32 v100, v100, v81
	v_sub_f32_e32 v101, v101, v81
	v_sub_f32_e32 v102, v102, v81
	v_sub_f32_e32 v103, v103, v81
	v_sub_f32_e32 v104, v104, v81
	v_sub_f32_e32 v105, v105, v81
	v_sub_f32_e32 v106, v106, v81
	v_sub_f32_e32 v107, v107, v81
	v_sub_f32_e32 v108, v108, v81
	v_sub_f32_e32 v109, v109, v81
	v_sub_f32_e32 v110, v110, v81
	v_sub_f32_e32 v111, v111, v81
	v_sub_f32_e32 v112, v112, v81
	v_sub_f32_e32 v113, v113, v81
	v_sub_f32_e32 v114, v114, v81
	v_sub_f32_e32 v115, v115, v81
	v_sub_f32_e32 v116, v116, v81
	v_sub_f32_e32 v117, v117, v81
	v_sub_f32_e32 v118, v118, v81
	v_sub_f32_e32 v119, v119, v81
	v_sub_f32_e32 v120, v120, v81
	v_sub_f32_e32 v121, v121, v81
	v_sub_f32_e32 v122, v122, v81
	v_sub_f32_e32 v123, v123, v81
	v_sub_f32_e32 v124, v124, v81
	v_sub_f32_e32 v125, v125, v81
	v_sub_f32_e32 v126, v126, v81
	v_sub_f32_e32 v127, v127, v81
	v_sub_f32_e32 v236, v236, v81
	v_sub_f32_e32 v237, v237, v81
	v_sub_f32_e32 v238, v238, v81
	v_sub_f32_e32 v239, v239, v81
	v_sub_f32_e32 v240, v240, v81
	v_sub_f32_e32 v241, v241, v81
	v_sub_f32_e32 v242, v242, v81
	v_sub_f32_e32 v243, v243, v81
	v_sub_f32_e32 v244, v244, v81
	v_sub_f32_e32 v245, v245, v81
	v_sub_f32_e32 v246, v246, v81
	v_sub_f32_e32 v247, v247, v81
	v_sub_f32_e32 v248, v248, v81
	v_sub_f32_e32 v249, v249, v81
	v_sub_f32_e32 v250, v250, v81
	v_sub_f32_e32 v251, v251, v81
	v_add_f32_e32 v222, v222, v81
	v_mul_f32_e32 v215, v215, v80
	s_branch .LBB0_843
